# P6 filler: W3B conversion items split in two stages so the 32 workgroups without an adaLN item take 8 more items per wave (guarded by grid==256)
# speedup vs baseline: 1.0084x; 1.0084x over previous
; #define GAS __attribute__((address_space(1)))
; #define LAS __attribute__((address_space(3)))
; #define MODI_LOAD(b, s) do { _Pragma("unroll") for (int i = 0; i < 4; ++i) buf[b][i] = __builtin_nontemporal_load((const GAS f32x4*)(Wb + (size_t)(32 * (s) + 16 * (i >> 1) + (i & 1)) * (MODW * 4) + wlo)); } while (0)
; #define MODI_ALOAD(r, s) do { const int s_ = (s) < nsteps ? (s) : nsteps - 1; ar[r][0] = *(const GAS v4u*)(Cb + (size_t)s_ * 9216 + c1); ar[r][1] = *(const GAS v4u*)(Cb + (size_t)s_ * 9216 + c2); } while (0)
; #define MODI_AWRITE(r, s) do { *(LAS v4u*)(la + ((s) & 1) * MODI_A_BYTES + c1) = ar[r][0]; *(LAS v4u*)(la + ((s) & 1) * MODI_A_BYTES + c2) = ar[r][1]; } while (0)
; #define SEAM(k) do { if (IN(k) && IN((k) + 1)) xcd_barrier(bar); } while (0)
; __device__ __forceinline__ void mod_item256(Frame& F, const Args& A, int cg, int k0, int nsteps, float* dst, int ldd, int dcol0, const float* bias) {
;     const int lane = F.lane, w = F.wave, n0 = 256 * cg + 32 * w, tid = F.tid;
;     LAS unsigned char* sb = F.lds + w * MODI_SB;
;     LAS unsigned char* la = F.lds + MODI_A_OFF;
;     const bf16* CS = (const bf16*)(A.ws + WS_CSI);
;     const int kp = lane >> 3, a8 = lane & 7, n4 = 4 * a8;
;     const GAS char* Wb = (const GAS char*)(A.in[I_WADA] + (size_t)k0 * MODW + n0);
;     const unsigned wlo = (unsigned)((2 * kp) * MODW + n4) * 4u;
;     const GAS char* Cb = (const GAS char*)CS + (size_t)(k0 / 32) * 9216;
;     const unsigned c1 = (unsigned)tid * 16u, c2 = (unsigned)(512 + (tid & 63)) * 16u;
;     f32x4 acc[9][2];
; #pragma unroll
;     for (int mt = 0; mt < 9; ++mt)
; #pragma unroll
;         for (int j = 0; j < 2; ++j) acc[mt][j] = (f32x4){0.f, 0.f, 0.f, 0.f};
;     f32x4 buf[2][4];
;     v4u ar[2][2];
;     ...
;     __syncthreads();
;     MODI_ALOAD(0, 0); MODI_ALOAD(1, 1);
;     MODI_LOAD(0, 0); MODI_LOAD(1, 1);
;     MODI_AWRITE(0, 0);
;     MODI_ALOAD(0, 2);
; __global__ void __launch_bounds__(NWAVES * 64, 2) mk_fwd(Args args) {
;     ...
;         if (rep == 0) { const int left8 = ((M / 256) * (NQ8 / 256)) % F.G;
;             if (cb >= left8) { const int ir = cb - left8, ni = F.G - left8;
;                 mod_chunk_partials(F, args, 2, ir, ni); __syncthreads(); { const int rank = ir * NWAVES + F.wave, nw = ni * NWAVES; conv_job<JOB_W3B>(F, args, rank, nw); } } } } } SEAM(6);
.LBB0_528:
	s_movk_i32 s99, 0x2b00
	s_mov_b32 s101, 1
	s_abs_i32 s0, s33
	v_cvt_f32_u32_e32 v2, s0
	s_sub_i32 s1, 0, s0
	v_rcp_iflag_f32_e32 v2, v2
	s_nop 0
	v_mul_f32_e32 v2, 0x4f7ffffe, v2
	v_cvt_u32_f32_e32 v2, v2
	s_nop 0
	v_readfirstlane_b32 s2, v2
	s_mul_i32 s1, s1, s2
	s_mul_hi_u32 s1, s2, s1
	s_add_i32 s2, s2, s1
	s_mul_hi_u32 s1, s2, 0x120
	s_mul_i32 s1, s1, s0
	s_sub_i32 s1, 0x120, s1
	s_sub_i32 s2, s1, s0
	s_cmp_ge_u32 s1, s0
	s_cselect_b32 s1, s2, s1
	s_sub_i32 s2, s1, s0
	s_cmp_ge_u32 s1, s0
	s_cselect_b32 s0, s2, s1
	s_cmp_lt_i32 s50, s0
	s_cbranch_scc1 .LBB0_551
	s_sub_i32 s1, s50, s0
	s_sub_i32 s0, s33, s0
	s_mov_b64 s[92:93], s[58:59]
	s_cmpk_gt_i32 s1, 0xbf
	v_lshrrev_b32_e32 v160, 5, v162
	s_cbranch_scc1 .LBB0_548
	v_lshrrev_b32_e32 v3, 2, v162
	s_add_u32 s22, s30, 0x63700000
	v_readlane_b32 s2, v252, 38
	v_lshlrev_b32_e32 v161, 2, v162
	v_and_b32_e32 v4, 14, v3
	s_addc_u32 s23, s31, 0
	s_lshl_b32 s34, s2, 5
	v_and_b32_e32 v2, 28, v161
	v_mul_u32_u24_e32 v4, 0x9000, v4
	s_mulk_i32 s2, 0xa00
	v_or_b32_e32 v4, v4, v2
	s_add_u32 s54, s30, 0x38d00000
	v_lshrrev_b32_e32 v5, 1, v162
	v_lshlrev_b32_e32 v122, 2, v4
	s_addc_u32 s55, s31, 0
	s_add_i32 s2, s2, 0
	v_and_b32_e32 v4, 3, v0
	v_and_b32_e32 v5, 12, v5
	v_add_u32_e32 v5, s2, v5
	v_mul_u32_u24_e32 v10, 0x50, v2
	v_bitop3_b32 v2, v160, v4, 2 bitop3:0x36
	v_lshl_add_u32 v11, v2, 4, v5
	v_and_b32_e32 v2, 12, v3
	v_mul_u32_u24_e32 v128, 0xc000, v2
	v_or_b32_e32 v2, 3, v3
	v_mul_u32_u24_e32 v132, 0xc000, v2
	v_or_b32_e32 v2, 19, v3
	v_mul_u32_u24_e32 v134, 0xc000, v2
	v_or_b32_e32 v2, 35, v3
	v_mul_u32_u24_e32 v136, 0xc000, v2
	v_or_b32_e32 v2, 51, v3
	v_mul_u32_u24_e32 v138, 0xc000, v2
	v_or_b32_e32 v2, 0x43, v3
	v_mul_u32_u24_e32 v144, 0xc000, v2
	v_or_b32_e32 v2, 0x53, v3
	v_mul_u32_u24_e32 v146, 0xc000, v2
	v_or_b32_e32 v2, 0x63, v3
	v_mul_u32_u24_e32 v148, 0xc000, v2
	v_or_b32_e32 v2, 0x73, v3
	v_readlane_b32 s76, v252, 19
	v_bitop3_b32 v9, v160, v0, 3 bitop3:0x78
	v_mul_u32_u24_e32 v150, 0xc000, v2
	v_readlane_b32 s80, v252, 23
	v_readlane_b32 s81, v252, 24
	v_lshrrev_b32_e32 v13, 6, v0
	s_mov_b32 s58, 0x24000
	v_mov_b64_e32 v[2:3], s[30:31]
	v_lshl_add_u32 v9, v9, 4, v5
	s_add_u32 s72, s30, 0x50000
	v_readlane_b32 s82, v252, 25
	v_readlane_b32 s83, v252, 26
	v_readlane_b32 s84, v252, 27
	v_readlane_b32 s85, v252, 28
	v_readlane_b32 s86, v252, 29
	v_readlane_b32 s87, v252, 30
	v_readlane_b32 s88, v252, 31
	v_readlane_b32 s89, v252, 32
	v_readlane_b32 s90, v252, 33
	v_readlane_b32 s91, v252, 34
	s_mov_b64 s[40:41], s[80:81]
	v_mad_u64_u32 v[4:5], s[10:11], v13, s58, v[2:3]
	v_bitop3_b32 v7, v161, 48, v0 bitop3:0x48
	s_mov_b32 s6, 0xc000
	s_addc_u32 s73, s31, 0
	s_mov_b64 s[48:49], s[88:89]
	s_mov_b64 s[10:11], 0x38f18000
	v_and_b32_e32 v6, 0x3f0, v164
	v_mov_b32_e32 v165, 0
	v_add_u32_e32 v7, s2, v7
	v_lshlrev_b32_e32 v8, 4, v162
	v_mul_u32_u24_e32 v12, 0x50, v190
	v_readlane_b32 s77, v252, 20
	v_readlane_b32 s78, v252, 21
	v_readlane_b32 s79, v252, 22
	s_add_u32 s8, s48, 0x18000
	v_lshl_add_u64 v[154:155], v[4:5], 0, s[10:11]
	v_mad_u64_u32 v[156:157], s[10:11], v13, s6, v[2:3]
	v_or_b32_e32 v124, 0x2000, v6
	v_mov_b32_e32 v125, v165
	v_mov_b32_e32 v123, v165
	s_mov_b32 s7, 0
	v_or_b32_e32 v126, s34, v190
	v_mov_b32_e32 v127, v165
	v_mov_b32_e32 v129, v165
	v_or_b32_e32 v130, 0xc000, v128
	v_mov_b32_e32 v131, v165
	v_mov_b32_e32 v133, v165
	v_mov_b32_e32 v135, v165
	v_mov_b32_e32 v137, v165
	v_mov_b32_e32 v139, v165
	v_or_b32_e32 v140, 0x300000, v128
	v_mov_b32_e32 v141, v165
	v_or_b32_e32 v142, 0x30c000, v128
	v_mov_b32_e32 v143, v165
	v_mov_b32_e32 v145, v165
	v_mov_b32_e32 v147, v165
	v_mov_b32_e32 v149, v165
	v_mov_b32_e32 v151, v165
	v_cmp_gt_u32_e64 s[2:3], 16, v162
	v_or_b32_e32 v152, 0x600000, v128
	v_mov_b32_e32 v153, v165
	s_mov_b64 s[42:43], s[82:83]
	s_mov_b64 s[44:45], s[84:85]
	s_mov_b64 s[46:47], s[86:87]
	s_mov_b64 s[50:51], s[90:91]
	s_addc_u32 s9, s49, 0
	v_or_b32_e32 v166, 0xfffffe00, v0
	s_mov_b32 s59, 0x240000
	s_mov_b32 s74, 0x480000
	v_add_u32_e32 v167, v9, v10
	v_add_u32_e32 v168, v11, v10
	s_mov_b32 s75, 0x900000
	s_mov_b32 s76, 0x924000
	s_mov_b32 s77, 0xb40000
	s_mov_b32 s78, 0xb64000
	v_add_u32_e32 v169, v7, v12
	v_add_u32_e32 v170, 0, v8
	s_mov_b32 s79, 0x3d8000
	s_mov_b32 s84, 0x48c000
	s_mov_b32 s85, 0x498000
	s_mov_b32 s86, 0x540000
	s_add_i32 s87, 0, 0x23140
	s_mov_b64 s[10:11], 0x120000
	s_mov_b64 s[12:13], 0x60000
	s_movk_i32 s88, 0x1e3f
	v_add_u32_e32 v171, 0, v164
	v_add_u32_e32 v172, 0, v6
	s_mov_b32 s89, s1
	s_branch .LBB0_532

; template <int MODE>
; __device__ __forceinline__ void p0_transpose_item8(const float* W, int K, int N, unsigned char* WT, float scale, LAS float* scr, int item, int lane) {
;     const int nblk = N / 32, kb = item / nblk, nb = item % nblk, k0 = 128 * kb, n0 = 32 * nb;
;     const GAS float* Wg = (const GAS float*)W;
; #pragma unroll
;     for (int h2 = 0; h2 < 2; ++h2) { float ld[32];
; #pragma unroll
; template <int JOB>
; __device__ __forceinline__ void conv_job(Frame& F, const Args& A, int rank, int nw) {
;     ...
;     for (int it = rank; it < N; it += nw) {
;         if constexpr (JOB == JOB_W1A) p0_transpose_item8<1>(A.in[I_W1A], D, FF, ws + WS_W13A, S_W13, scr, it, F.lane);
;         if constexpr (JOB == JOB_W3A) p0_transpose_item8<2>(A.in[I_W3A], D, FF, ws + WS_W13A, S_W13, scr, it, F.lane);
;         if constexpr (JOB == JOB_W2A) p0_transpose_item8<0>(A.in[I_W2A], FF, D, ws + WS_W2A, S_W2, scr, it, F.lane);
;         if constexpr (JOB == JOB_WIN) { p0_transpose_item<0>(A.in[I_WIN], D, NPROJ, (bf16*)(ws + WS_WIN), scr, it, F.lane);
;             const int nb = it % (NPROJ / 32), kb = it / (NPROJ / 32);
;             if (32 * nb < NQ8) { const int n = F.lane & 31;
; #pragma unroll
;                 for (int p = 0; p < 2; ++p) { const int q = 2 * p + (F.lane >> 5); const LAS float* t = scr + (16 * q) * 33 + n;
;                     v4u o;
;                     o.x = pg8::cvt4_fp8(t[0 * 33] * S_W13, t[1 * 33] * S_W13, t[2 * 33] * S_W13, t[3 * 33] * S_W13);
;                     o.y = pg8::cvt4_fp8(t[4 * 33] * S_W13, t[5 * 33] * S_W13, t[6 * 33] * S_W13, t[7 * 33] * S_W13);
;                     o.z = pg8::cvt4_fp8(t[8 * 33] * S_W13, t[9 * 33] * S_W13, t[10 * 33] * S_W13, t[11 * 33] * S_W13);
;                     o.w = pg8::cvt4_fp8(t[12 * 33] * S_W13, t[13 * 33] * S_W13, t[14 * 33] * S_W13, t[15 * 33] * S_W13);
;                     *(GAS v4u*)(ws + WS_WIN8 + (size_t)(32 * nb + n) * D + 64 * kb + 16 * q) = o; }
;                 LDS_WAIT(); asm volatile("" ::: "memory"); } }
;         if constexpr (JOB == JOB_WOUT) p0_transpose_item<0>(A.in[I_WOUT], D, D, (bf16*)(ws + WS_WOUT), scr, it, F.lane);
;         if constexpr (JOB == JOB_W1B) p0_transpose_item8<1>(A.in[I_W1B], D, FF, ws + WS_W13B, S_W13, scr, it, F.lane);
;         if constexpr (JOB == JOB_W3B) p0_transpose_item8<2>(A.in[I_W3B], D, FF, ws + WS_W13B, S_W13, scr, it, F.lane);
.LBB0_548:
	s_lshl_b32 s1, s1, 3
	v_readlane_b32 s2, v252, 38
	s_add_i32 s1, s1, s2
	s_mov_b32 s100, s1
	s_cmpk_eq_i32 s33, 0x100
	s_cbranch_scc0 .Lq_nosplit
	s_movk_i32 s99, 0x2300
	s_mov_b32 s101, 0
.Lq_nosplit:
	v_readlane_b32 s94, v252, 39
	s_cmpk_gt_i32 s1, 0x2aff
	v_readlane_b32 s95, v252, 40
	s_mov_b64 s[58:59], s[92:93]
	s_mov_b32 s51, s70
	s_waitcnt vmcnt(0)
	s_barrier
	s_cbranch_scc1 .LBB0_551
	v_readlane_b32 s2, v252, 38
	s_mulk_i32 s2, 0x4200
	v_and_b32_e32 v22, 31, v0
	v_readlane_b32 s72, v252, 19
	s_add_i32 s2, s2, 0
	v_lshlrev_b32_e32 v18, 2, v22
	v_mov_b32_e32 v19, 0
	v_readlane_b32 s78, v252, 25
	v_readlane_b32 s79, v252, 26
	v_add_u32_e32 v2, s2, v18
	s_movk_i32 s2, 0x84
	v_lshl_add_u64 v[20:21], s[78:79], 0, v[18:19]
	v_and_b32_e32 v18, 16, v163
	v_mul_u32_u24_e32 v3, 0x84, v18
	v_mad_u32_u24 v23, v160, s2, v2
	v_add_u32_e32 v24, v2, v3
	s_lshl_b32 s8, s0, 3
	s_lshl_b32 s9, s1, 5
	s_lshl_b32 s0, s0, 8
	s_mov_b32 s10, 0xac00
	s_mov_b32 s11, 0xc3e00000
	v_mov_b32_e32 v25, 0x43e00000
	v_add_u32_e32 v26, 0x400, v23
	v_add_u32_e32 v27, 0x800, v23
	v_add_u32_e32 v28, 0xc00, v23
	v_add_u32_e32 v29, 0x1000, v23
	v_add_u32_e32 v30, 0x1400, v23
	v_add_u32_e32 v31, 0x1800, v23
	v_add_u32_e32 v32, 0x1c00, v23
	v_add_u32_e32 v33, 0x2000, v23
	v_add_u32_e32 v34, 0x2200, v23
	v_add_u32_e32 v35, 0x2400, v23
	v_add_u32_e32 v36, 0x2600, v23
	v_add_u32_e32 v37, 0x2800, v23
	v_add_u32_e32 v38, 0x2a00, v23
	v_add_u32_e32 v39, 0x2c00, v23
	v_add_u32_e32 v40, 0x2e00, v23
	v_add_u32_e32 v41, 0x3000, v23
	v_add_u32_e32 v42, 0x3200, v23
	v_add_u32_e32 v43, 0x3400, v23
	v_add_u32_e32 v44, 0x3600, v23
	v_add_u32_e32 v45, 0x3800, v23
	v_add_u32_e32 v46, 0x3a00, v23
	v_add_u32_e32 v47, 0x3c00, v23
	v_add_u32_e32 v48, 0x3e00, v23
	v_add_u32_e32 v49, 0x400, v24
	v_add_u32_e32 v50, 0x1000, v24
	v_add_u32_e32 v51, 0x1200, v24
	v_add_u32_e32 v52, 0x1400, v24
	v_add_u32_e32 v53, 0x1600, v24
	v_add_u32_e32 v54, 0x2000, v24
	v_add_u32_e32 v55, 0x2400, v24
	v_add_u32_e32 v56, 0x2800, v24
	v_add_u32_e32 v57, 0x3000, v24
	v_add_u32_e32 v58, 0x3200, v24
	v_add_u32_e32 v59, 0x3400, v24
	v_add_u32_e32 v60, 0x3600, v24
	v_add_u32_e32 v61, 0x3800, v24
	v_readlane_b32 s73, v252, 20
	v_readlane_b32 s74, v252, 21
	v_readlane_b32 s75, v252, 22
	v_readlane_b32 s76, v252, 23
	v_readlane_b32 s77, v252, 24
	v_readlane_b32 s80, v252, 27
	v_readlane_b32 s81, v252, 28
	v_readlane_b32 s82, v252, 29
	v_readlane_b32 s83, v252, 30
	v_readlane_b32 s84, v252, 31
	v_readlane_b32 s85, v252, 32
	v_readlane_b32 s86, v252, 33
	v_readlane_b32 s87, v252, 34
.LBB0_550:
	s_mul_hi_i32 s2, s1, 0x2fa0be83
	s_lshr_b32 s3, s2, 31
	s_ashr_i32 s2, s2, 6
	s_add_i32 s3, s2, s3
	s_mul_i32 s6, s3, 0xfffffea8
	s_lshl_b32 s2, s3, 7
	s_mulk_i32 s3, 0xd500
	s_add_i32 s12, s1, s6
	s_add_i32 s6, s9, s3
	v_or_b32_e32 v64, s2, v160
	s_ashr_i32 s7, s6, 31
	v_or_b32_e32 v66, 2, v64
	v_or_b32_e32 v68, 4, v64
	v_or_b32_e32 v70, 6, v64
	v_or_b32_e32 v72, 8, v64
	v_or_b32_e32 v74, 10, v64
	v_or_b32_e32 v76, 12, v64
	v_or_b32_e32 v78, 14, v64
	v_or_b32_e32 v80, 16, v64
	v_or_b32_e32 v82, 18, v64
	v_or_b32_e32 v84, 20, v64
	v_or_b32_e32 v86, 22, v64
	v_or_b32_e32 v88, 24, v64
	v_or_b32_e32 v90, 26, v64
	v_or_b32_e32 v92, 28, v64
	v_or_b32_e32 v94, 30, v64
	v_or_b32_e32 v96, 32, v64
	v_or_b32_e32 v98, 34, v64
	v_or_b32_e32 v100, 36, v64
	v_or_b32_e32 v102, 38, v64
	v_or_b32_e32 v104, 40, v64
	v_or_b32_e32 v106, 42, v64
	v_or_b32_e32 v108, 44, v64
	v_or_b32_e32 v110, 46, v64
	v_or_b32_e32 v112, 48, v64
	v_or_b32_e32 v114, 50, v64
	v_or_b32_e32 v116, 52, v64
	v_or_b32_e32 v118, 54, v64
	v_or_b32_e32 v120, 56, v64
	v_or_b32_e32 v122, 58, v64
	v_or_b32_e32 v124, 60, v64
	v_or_b32_e32 v126, 62, v64
	s_bfe_u32 s13, s12, 0x2001d
	v_lshl_add_u64 v[62:63], s[6:7], 2, v[20:21]
	v_or_b32_e32 v128, 64, v64
	v_or_b32_e32 v130, 0x42, v64
	v_or_b32_e32 v132, 0x44, v64
	v_or_b32_e32 v134, 0x46, v64
	v_or_b32_e32 v136, 0x48, v64
	v_or_b32_e32 v138, 0x4a, v64
	v_or_b32_e32 v140, 0x4c, v64
	v_or_b32_e32 v142, 0x4e, v64
	v_or_b32_e32 v144, 0x50, v64
	v_or_b32_e32 v146, 0x52, v64
	v_or_b32_e32 v148, 0x54, v64
	v_or_b32_e32 v150, 0x56, v64
	v_or_b32_e32 v152, 0x58, v64
	v_or_b32_e32 v154, 0x5a, v64
	v_or_b32_e32 v156, 0x5c, v64
	v_or_b32_e32 v158, 0x5e, v64
	v_or_b32_e32 v161, 0x60, v64
	v_or_b32_e32 v163, 0x62, v64
	v_or_b32_e32 v165, 0x64, v64
	v_or_b32_e32 v172, 0x66, v64
	v_or_b32_e32 v174, 0x68, v64
	v_or_b32_e32 v176, 0x6a, v64
	v_or_b32_e32 v178, 0x6c, v64
	v_or_b32_e32 v180, 0x6e, v64
	v_or_b32_e32 v182, 0x70, v64
	v_or_b32_e32 v184, 0x72, v64
	v_or_b32_e32 v186, 0x74, v64
	v_or_b32_e32 v188, 0x76, v64
	v_or_b32_e32 v190, 0x78, v64
	v_or_b32_e32 v192, 0x7a, v64
	v_or_b32_e32 v194, 0x7c, v64
	v_or_b32_e32 v196, 0x7e, v64
	s_add_i32 s7, s12, s13
	v_mad_i64_i32 v[64:65], s[12:13], v64, s10, v[62:63]
	v_mad_i64_i32 v[66:67], s[12:13], v66, s10, v[62:63]
	v_mad_i64_i32 v[68:69], s[12:13], v68, s10, v[62:63]
	v_mad_i64_i32 v[70:71], s[12:13], v70, s10, v[62:63]
	v_mad_i64_i32 v[72:73], s[12:13], v72, s10, v[62:63]
	v_mad_i64_i32 v[74:75], s[12:13], v74, s10, v[62:63]
	v_mad_i64_i32 v[76:77], s[12:13], v76, s10, v[62:63]
	v_mad_i64_i32 v[78:79], s[12:13], v78, s10, v[62:63]
	v_mad_i64_i32 v[80:81], s[12:13], v80, s10, v[62:63]
	v_mad_i64_i32 v[82:83], s[12:13], v82, s10, v[62:63]
	v_mad_i64_i32 v[84:85], s[12:13], v84, s10, v[62:63]
	v_mad_i64_i32 v[86:87], s[12:13], v86, s10, v[62:63]
	v_mad_i64_i32 v[88:89], s[12:13], v88, s10, v[62:63]
	v_mad_i64_i32 v[90:91], s[12:13], v90, s10, v[62:63]
	v_mad_i64_i32 v[92:93], s[12:13], v92, s10, v[62:63]
	v_mad_i64_i32 v[94:95], s[12:13], v94, s10, v[62:63]
	v_mad_i64_i32 v[96:97], s[12:13], v96, s10, v[62:63]
; template <int MODE>
; __device__ __forceinline__ void p0_transpose_item8(const float* W, int K, int N, unsigned char* WT, float scale, LAS float* scr, int item, int lane) {
;     ...
;     for (int h2 = 0; h2 < 2; ++h2) { float ld[32];
; #pragma unroll
;         for (int i = 0; i < 32; ++i) { const int kk = 2 * (i + 32 * h2) + (lane >> 5); ld[i] = __builtin_nontemporal_load(&Wg[(size_t)(k0 + kk) * N + n0 + (lane & 31)]); }
; #pragma unroll
;         for (int i = 0; i < 32; ++i) { const int kk = 2 * (i + 32 * h2) + (lane >> 5); scr[kk * 33 + (lane & 31)] = ld[i]; } }
	v_mad_i64_i32 v[98:99], s[12:13], v98, s10, v[62:63]
	v_mad_i64_i32 v[100:101], s[12:13], v100, s10, v[62:63]
	v_mad_i64_i32 v[102:103], s[12:13], v102, s10, v[62:63]
	v_mad_i64_i32 v[104:105], s[12:13], v104, s10, v[62:63]
	v_mad_i64_i32 v[106:107], s[12:13], v106, s10, v[62:63]
	v_mad_i64_i32 v[108:109], s[12:13], v108, s10, v[62:63]
	v_mad_i64_i32 v[110:111], s[12:13], v110, s10, v[62:63]
	v_mad_i64_i32 v[112:113], s[12:13], v112, s10, v[62:63]
	v_mad_i64_i32 v[114:115], s[12:13], v114, s10, v[62:63]
	v_mad_i64_i32 v[116:117], s[12:13], v116, s10, v[62:63]
	v_mad_i64_i32 v[118:119], s[12:13], v118, s10, v[62:63]
	v_mad_i64_i32 v[120:121], s[12:13], v120, s10, v[62:63]
	v_mad_i64_i32 v[122:123], s[12:13], v122, s10, v[62:63]
	v_mad_i64_i32 v[124:125], s[12:13], v124, s10, v[62:63]
	v_mad_i64_i32 v[126:127], s[12:13], v126, s10, v[62:63]
	v_mad_i64_i32 v[128:129], s[12:13], v128, s10, v[62:63]
	v_mad_i64_i32 v[130:131], s[12:13], v130, s10, v[62:63]
	v_mad_i64_i32 v[132:133], s[12:13], v132, s10, v[62:63]
	v_mad_i64_i32 v[134:135], s[12:13], v134, s10, v[62:63]
	v_mad_i64_i32 v[136:137], s[12:13], v136, s10, v[62:63]
	v_mad_i64_i32 v[138:139], s[12:13], v138, s10, v[62:63]
	v_mad_i64_i32 v[140:141], s[12:13], v140, s10, v[62:63]
	v_mad_i64_i32 v[142:143], s[12:13], v142, s10, v[62:63]
	v_mad_i64_i32 v[144:145], s[12:13], v144, s10, v[62:63]
	v_mad_i64_i32 v[146:147], s[12:13], v146, s10, v[62:63]
	v_mad_i64_i32 v[148:149], s[12:13], v148, s10, v[62:63]
	v_mad_i64_i32 v[150:151], s[12:13], v150, s10, v[62:63]
	v_mad_i64_i32 v[152:153], s[12:13], v152, s10, v[62:63]
	v_mad_i64_i32 v[154:155], s[12:13], v154, s10, v[62:63]
	v_mad_i64_i32 v[156:157], s[12:13], v156, s10, v[62:63]
	v_mad_i64_i32 v[158:159], s[12:13], v158, s10, v[62:63]
	v_mad_i64_i32 v[166:167], s[12:13], v161, s10, v[62:63]
	v_mad_i64_i32 v[168:169], s[12:13], v163, s10, v[62:63]
	v_mad_i64_i32 v[170:171], s[12:13], v165, s10, v[62:63]
	v_mad_i64_i32 v[172:173], s[12:13], v172, s10, v[62:63]
	v_mad_i64_i32 v[174:175], s[12:13], v174, s10, v[62:63]
	v_mad_i64_i32 v[176:177], s[12:13], v176, s10, v[62:63]
	v_mad_i64_i32 v[178:179], s[12:13], v178, s10, v[62:63]
	v_mad_i64_i32 v[180:181], s[12:13], v180, s10, v[62:63]
	v_mad_i64_i32 v[182:183], s[12:13], v182, s10, v[62:63]
	v_mad_i64_i32 v[184:185], s[12:13], v184, s10, v[62:63]
	v_mad_i64_i32 v[186:187], s[12:13], v186, s10, v[62:63]
	v_mad_i64_i32 v[188:189], s[12:13], v188, s10, v[62:63]
	v_mad_i64_i32 v[190:191], s[12:13], v190, s10, v[62:63]
	v_mad_i64_i32 v[192:193], s[12:13], v192, s10, v[62:63]
	v_mad_i64_i32 v[194:195], s[12:13], v194, s10, v[62:63]
	v_mad_i64_i32 v[62:63], s[12:13], v196, s10, v[62:63]
	global_load_dword v64, v[64:65], off nt
	s_nop 0
	global_load_dword v65, v[66:67], off nt
	s_nop 0
	global_load_dword v66, v[68:69], off nt
	global_load_dword v67, v[70:71], off nt
	s_nop 0
	global_load_dword v68, v[72:73], off nt
	global_load_dword v69, v[74:75], off nt
	global_load_dword v70, v[76:77], off nt
	global_load_dword v71, v[78:79], off nt
	s_nop 0
	global_load_dword v72, v[80:81], off nt
	global_load_dword v73, v[82:83], off nt
	global_load_dword v74, v[84:85], off nt
	global_load_dword v75, v[86:87], off nt
	global_load_dword v76, v[88:89], off nt
	global_load_dword v77, v[90:91], off nt
	global_load_dword v78, v[92:93], off nt
	global_load_dword v79, v[94:95], off nt
	global_load_dword v80, v[96:97], off nt
	global_load_dword v81, v[98:99], off nt
	global_load_dword v82, v[100:101], off nt
	global_load_dword v83, v[102:103], off nt
	global_load_dword v84, v[104:105], off nt
	global_load_dword v85, v[106:107], off nt
	global_load_dword v86, v[108:109], off nt
	global_load_dword v87, v[110:111], off nt
	global_load_dword v88, v[112:113], off nt
	global_load_dword v89, v[114:115], off nt
	global_load_dword v90, v[116:117], off nt
	global_load_dword v91, v[118:119], off nt
	global_load_dword v92, v[120:121], off nt
	global_load_dword v93, v[122:123], off nt
	global_load_dword v94, v[124:125], off nt
	global_load_dword v95, v[126:127], off nt
	global_load_dword v96, v[128:129], off nt
	global_load_dword v97, v[130:131], off nt
	global_load_dword v98, v[132:133], off nt
	global_load_dword v99, v[134:135], off nt
	global_load_dword v100, v[136:137], off nt
	global_load_dword v101, v[138:139], off nt
	global_load_dword v102, v[140:141], off nt
	global_load_dword v103, v[142:143], off nt
	global_load_dword v104, v[144:145], off nt
	global_load_dword v105, v[146:147], off nt
	global_load_dword v106, v[148:149], off nt
	global_load_dword v107, v[150:151], off nt
	global_load_dword v108, v[152:153], off nt
	global_load_dword v109, v[154:155], off nt
	global_load_dword v110, v[156:157], off nt
	global_load_dword v111, v[158:159], off nt
	global_load_dword v112, v[166:167], off nt
	global_load_dword v113, v[168:169], off nt
	global_load_dword v114, v[170:171], off nt
	global_load_dword v115, v[172:173], off nt
	global_load_dword v116, v[174:175], off nt
	global_load_dword v117, v[176:177], off nt
	global_load_dword v118, v[178:179], off nt
	global_load_dword v119, v[180:181], off nt
	global_load_dword v120, v[182:183], off nt
	global_load_dword v121, v[184:185], off nt
	global_load_dword v122, v[186:187], off nt
	global_load_dword v123, v[188:189], off nt
	global_load_dword v124, v[190:191], off nt
	global_load_dword v125, v[192:193], off nt
	global_load_dword v126, v[194:195], off nt
	global_load_dword v127, v[62:63], off nt
	s_waitcnt vmcnt(62)
	ds_write2_b32 v23, v64, v65 offset1:66
	s_waitcnt vmcnt(60)
	ds_write2_b32 v23, v66, v67 offset0:132 offset1:198
	s_waitcnt vmcnt(58)
; #define LAS __attribute__((address_space(3)))
; #define LDS_WAIT() asm volatile("s_waitcnt lgkmcnt(0)" ::: "memory")
; template <int MODE>
; __device__ __forceinline__ void p0_transpose_item8(const float* W, int K, int N, unsigned char* WT, float scale, LAS float* scr, int item, int lane) {
;     ...
;         for (int i = 0; i < 32; ++i) { const int kk = 2 * (i + 32 * h2) + (lane >> 5); scr[kk * 33 + (lane & 31)] = ld[i]; } }
;     LDS_WAIT(); asm volatile("" ::: "memory");
;     const int n = lane & 31, hf = lane >> 5;
;     const int r0 = (MODE == 0) ? n0 : (n0 / 128) * 256 + (n0 % 128) + (MODE == 2 ? 128 : 0);
; #pragma unroll
;     for (int p = 0; p < 4; ++p) { const int q = 2 * p + hf; const LAS float* s = scr + (16 * q) * 33 + n;
;         v4u o;
;         o.x = pg8::cvt4_fp8(s[0 * 33] * scale, s[1 * 33] * scale, s[2 * 33] * scale, s[3 * 33] * scale);
;         o.y = pg8::cvt4_fp8(s[4 * 33] * scale, s[5 * 33] * scale, s[6 * 33] * scale, s[7 * 33] * scale);
;         o.z = pg8::cvt4_fp8(s[8 * 33] * scale, s[9 * 33] * scale, s[10 * 33] * scale, s[11 * 33] * scale);
;         o.w = pg8::cvt4_fp8(s[12 * 33] * scale, s[13 * 33] * scale, s[14 * 33] * scale, s[15 * 33] * scale);
	ds_write2_b32 v26, v68, v69 offset0:8 offset1:74
	s_waitcnt vmcnt(56)
	ds_write2_b32 v26, v70, v71 offset0:140 offset1:206
	s_waitcnt vmcnt(54)
	ds_write2_b32 v27, v72, v73 offset0:16 offset1:82
	s_waitcnt vmcnt(52)
	ds_write2_b32 v27, v74, v75 offset0:148 offset1:214
	s_waitcnt vmcnt(50)
	ds_write2_b32 v28, v76, v77 offset0:24 offset1:90
	s_waitcnt vmcnt(48)
	ds_write2_b32 v28, v78, v79 offset0:156 offset1:222
	s_waitcnt vmcnt(46)
	ds_write2_b32 v29, v80, v81 offset0:32 offset1:98
	s_waitcnt vmcnt(44)
	ds_write2_b32 v29, v82, v83 offset0:164 offset1:230
	s_waitcnt vmcnt(42)
	ds_write2_b32 v30, v84, v85 offset0:40 offset1:106
	s_waitcnt vmcnt(40)
	ds_write2_b32 v30, v86, v87 offset0:172 offset1:238
	s_waitcnt vmcnt(38)
	ds_write2_b32 v31, v88, v89 offset0:48 offset1:114
	s_waitcnt vmcnt(36)
	ds_write2_b32 v31, v90, v91 offset0:180 offset1:246
	s_waitcnt vmcnt(34)
	ds_write2_b32 v32, v92, v93 offset0:56 offset1:122
	s_waitcnt vmcnt(32)
	ds_write2_b32 v32, v94, v95 offset0:188 offset1:254
	s_waitcnt vmcnt(30)
	ds_write2_b32 v33, v96, v97 offset0:64 offset1:130
	s_waitcnt vmcnt(28)
	ds_write2_b32 v34, v98, v99 offset0:68 offset1:134
	s_waitcnt vmcnt(26)
	ds_write2_b32 v35, v100, v101 offset0:72 offset1:138
	s_waitcnt vmcnt(24)
	ds_write2_b32 v36, v102, v103 offset0:76 offset1:142
	s_waitcnt vmcnt(22)
	ds_write2_b32 v37, v104, v105 offset0:80 offset1:146
	s_waitcnt vmcnt(20)
	ds_write2_b32 v38, v106, v107 offset0:84 offset1:150
	s_waitcnt vmcnt(18)
	ds_write2_b32 v39, v108, v109 offset0:88 offset1:154
	s_waitcnt vmcnt(16)
	ds_write2_b32 v40, v110, v111 offset0:92 offset1:158
	s_waitcnt vmcnt(14)
	ds_write2_b32 v41, v112, v113 offset0:96 offset1:162
	s_waitcnt vmcnt(12)
	ds_write2_b32 v42, v114, v115 offset0:100 offset1:166
	s_waitcnt vmcnt(10)
	ds_write2_b32 v43, v116, v117 offset0:104 offset1:170
	s_waitcnt vmcnt(8)
	ds_write2_b32 v44, v118, v119 offset0:108 offset1:174
	s_waitcnt vmcnt(6)
	ds_write2_b32 v45, v120, v121 offset0:112 offset1:178
	s_waitcnt vmcnt(4)
	ds_write2_b32 v46, v122, v123 offset0:116 offset1:182
	s_waitcnt vmcnt(2)
	ds_write2_b32 v47, v124, v125 offset0:120 offset1:186
	s_waitcnt vmcnt(0)
	ds_write2_b32 v48, v126, v127 offset0:124 offset1:190
	s_bfe_u32 s14, s6, 0x70018
	s_waitcnt lgkmcnt(0)
	s_add_i32 s14, s6, s14
	s_and_b32 s12, s14, 0xff80
	ds_read2_b32 v[64:65], v24 offset1:33
	ds_read2_b32 v[66:67], v24 offset0:66 offset1:99
	ds_read2_b32 v[68:69], v24 offset0:132 offset1:165
	ds_read2_b32 v[70:71], v24 offset0:198 offset1:231
	ds_read2_b32 v[72:73], v49 offset0:8 offset1:41
	ds_read2_b32 v[74:75], v49 offset0:74 offset1:107
	ds_read2_b32 v[76:77], v49 offset0:140 offset1:173
	ds_read2_b32 v[78:79], v49 offset0:206 offset1:239
	ds_read2_b32 v[80:81], v50 offset0:32 offset1:65
	ds_read2_b32 v[82:83], v50 offset0:98 offset1:131
	ds_read2_b32 v[84:85], v50 offset0:164 offset1:197
	ds_read2_b32 v[86:87], v51 offset0:102 offset1:135
	ds_read2_b32 v[88:89], v52 offset0:40 offset1:73
	ds_read2_b32 v[90:91], v52 offset0:106 offset1:139
	ds_read2_b32 v[92:93], v52 offset0:172 offset1:205
	ds_read2_b32 v[94:95], v53 offset0:110 offset1:143
	ds_read2_b32 v[96:97], v54 offset0:64 offset1:97
	ds_read2_b32 v[98:99], v54 offset0:130 offset1:163
	ds_read2_b32 v[100:101], v54 offset0:196 offset1:229
	ds_read2_b32 v[102:103], v55 offset0:6 offset1:39
	ds_read2_b32 v[104:105], v55 offset0:72 offset1:105
	ds_read2_b32 v[106:107], v55 offset0:138 offset1:171
	ds_read2_b32 v[108:109], v55 offset0:204 offset1:237
	ds_read2_b32 v[110:111], v56 offset0:14 offset1:47
	ds_read2_b32 v[112:113], v57 offset0:96 offset1:129
	ds_read2_b32 v[114:115], v57 offset0:162 offset1:195
	ds_read2_b32 v[116:117], v58 offset0:100 offset1:133
	ds_read2_b32 v[118:119], v59 offset0:38 offset1:71
	ds_read2_b32 v[120:121], v59 offset0:104 offset1:137
	ds_read2_b32 v[122:123], v59 offset0:170 offset1:203
	ds_read2_b32 v[124:125], v60 offset0:108 offset1:141
	ds_read2_b32 v[126:127], v61 offset0:46 offset1:79
	s_sext_i32_i16 s7, s7
	s_sub_i32 s6, s6, s12
	s_waitcnt lgkmcnt(14)
	v_mul_f32_e32 v64, 0x44000000, v64
	v_mul_f32_e32 v65, 0x44000000, v65
	v_mul_f32_e32 v68, 0x44000000, v68
	v_mul_f32_e32 v69, 0x44000000, v69
	v_mul_f32_e32 v72, 0x44000000, v72
	v_mul_f32_e32 v73, 0x44000000, v73
	v_mul_f32_e32 v76, 0x44000000, v76
	v_mul_f32_e32 v77, 0x44000000, v77
	v_mov_b32_e32 v2, 0
	v_mov_b32_e32 v3, 0
	v_mov_b32_e32 v4, 0
	v_mov_b32_e32 v5, 0
	s_lshl_b32 s7, s7, 6
	s_addk_i32 s6, 0x80
	v_mul_f32_e32 v80, 0x44000000, v80
	v_mul_f32_e32 v81, 0x44000000, v81
	v_mul_f32_e32 v84, 0x44000000, v84
	v_mul_f32_e32 v85, 0x44000000, v85
	v_mul_f32_e32 v88, 0x44000000, v88
	v_mul_f32_e32 v89, 0x44000000, v89
	v_mul_f32_e32 v92, 0x44000000, v92
	v_mul_f32_e32 v93, 0x44000000, v93
	v_med3_f32 v64, v64, s11, v25
	v_med3_f32 v65, v65, s11, v25
	v_med3_f32 v68, v68, s11, v25
	v_med3_f32 v69, v69, s11, v25
	v_med3_f32 v72, v72, s11, v25
	v_med3_f32 v73, v73, s11, v25
	v_med3_f32 v76, v76, s11, v25
	v_med3_f32 v77, v77, s11, v25
	v_mov_b32_e32 v6, 0
	v_mov_b32_e32 v7, 0
	v_mov_b32_e32 v8, 0
	v_mov_b32_e32 v9, 0
	s_and_b32 s7, s7, 0xffffff00
	s_and_b32 s6, s6, 0xffff
	v_mul_f32_e32 v96, 0x44000000, v96
	v_mul_f32_e32 v97, 0x44000000, v97
	s_waitcnt lgkmcnt(13)
	v_mul_f32_e32 v100, 0x44000000, v100
	v_mul_f32_e32 v101, 0x44000000, v101
	s_waitcnt lgkmcnt(11)
	v_mul_f32_e32 v104, 0x44000000, v104
	v_mul_f32_e32 v105, 0x44000000, v105
	s_waitcnt lgkmcnt(9)
; #define GAS __attribute__((address_space(1)))
; #define LAS __attribute__((address_space(3)))
; #define LDS_WAIT() asm volatile("s_waitcnt lgkmcnt(0)" ::: "memory")
; template <int MODE>
; __device__ __forceinline__ void p0_transpose_item8(const float* W, int K, int N, unsigned char* WT, float scale, LAS float* scr, int item, int lane) {
;     ...
;     for (int p = 0; p < 4; ++p) { const int q = 2 * p + hf; const LAS float* s = scr + (16 * q) * 33 + n;
;         v4u o;
;         o.x = pg8::cvt4_fp8(s[0 * 33] * scale, s[1 * 33] * scale, s[2 * 33] * scale, s[3 * 33] * scale);
;         o.y = pg8::cvt4_fp8(s[4 * 33] * scale, s[5 * 33] * scale, s[6 * 33] * scale, s[7 * 33] * scale);
;         o.z = pg8::cvt4_fp8(s[8 * 33] * scale, s[9 * 33] * scale, s[10 * 33] * scale, s[11 * 33] * scale);
;         o.w = pg8::cvt4_fp8(s[12 * 33] * scale, s[13 * 33] * scale, s[14 * 33] * scale, s[15 * 33] * scale);
;         *(GAS v4u*)(WT + (size_t)(r0 + n) * K + k0 + 16 * q) = o; }
;     LDS_WAIT(); asm volatile("" ::: "memory");
; template <int JOB>
; __device__ __forceinline__ void conv_job(Frame& F, const Args& A, int rank, int nw) {
;     ...
;     for (int it = rank; it < N; it += nw) {
	v_mul_f32_e32 v108, 0x44000000, v108
	v_mul_f32_e32 v109, 0x44000000, v109
	v_med3_f32 v80, v80, s11, v25
	v_med3_f32 v81, v81, s11, v25
	v_med3_f32 v84, v84, s11, v25
	v_med3_f32 v85, v85, s11, v25
	v_med3_f32 v88, v88, s11, v25
	v_med3_f32 v89, v89, s11, v25
	v_med3_f32 v92, v92, s11, v25
	v_med3_f32 v93, v93, s11, v25
	v_cvt_pk_fp8_f32 v2, v64, v65
	v_cvt_pk_fp8_f32 v3, v68, v69
	v_cvt_pk_fp8_f32 v4, v72, v73
	v_cvt_pk_fp8_f32 v5, v76, v77
	v_mov_b32_e32 v10, 0
	v_mov_b32_e32 v11, 0
	v_mov_b32_e32 v12, 0
	v_mov_b32_e32 v13, 0
	s_add_i32 s7, s7, s6
	s_waitcnt lgkmcnt(7)
	v_mul_f32_e32 v112, 0x44000000, v112
	v_mul_f32_e32 v113, 0x44000000, v113
	s_waitcnt lgkmcnt(5)
	v_mul_f32_e32 v116, 0x44000000, v116
	v_mul_f32_e32 v117, 0x44000000, v117
	s_waitcnt lgkmcnt(3)
	v_mul_f32_e32 v120, 0x44000000, v120
	v_mul_f32_e32 v121, 0x44000000, v121
	s_waitcnt lgkmcnt(1)
	v_mul_f32_e32 v124, 0x44000000, v124
	v_mul_f32_e32 v125, 0x44000000, v125
	v_med3_f32 v96, v96, s11, v25
	v_med3_f32 v97, v97, s11, v25
	v_med3_f32 v100, v100, s11, v25
	v_med3_f32 v101, v101, s11, v25
	v_med3_f32 v104, v104, s11, v25
	v_med3_f32 v105, v105, s11, v25
	v_med3_f32 v108, v108, s11, v25
	v_med3_f32 v109, v109, s11, v25
	v_cvt_pk_fp8_f32 v6, v80, v81
	v_cvt_pk_fp8_f32 v7, v84, v85
	v_cvt_pk_fp8_f32 v8, v88, v89
	v_cvt_pk_fp8_f32 v9, v92, v93
	v_mov_b32_e32 v14, 0
	v_mov_b32_e32 v15, 0
	v_mov_b32_e32 v16, 0
	v_mov_b32_e32 v17, 0
	v_or_b32_e32 v62, s7, v22
	v_mul_f32_e32 v66, 0x44000000, v66
	v_mul_f32_e32 v67, 0x44000000, v67
	v_mul_f32_e32 v70, 0x44000000, v70
	v_mul_f32_e32 v71, 0x44000000, v71
	v_mul_f32_e32 v74, 0x44000000, v74
	v_mul_f32_e32 v75, 0x44000000, v75
	v_mul_f32_e32 v78, 0x44000000, v78
	v_mul_f32_e32 v79, 0x44000000, v79
	v_med3_f32 v112, v112, s11, v25
	v_med3_f32 v113, v113, s11, v25
	v_med3_f32 v116, v116, s11, v25
	v_med3_f32 v117, v117, s11, v25
	v_med3_f32 v120, v120, s11, v25
	v_med3_f32 v121, v121, s11, v25
	v_med3_f32 v124, v124, s11, v25
	v_med3_f32 v125, v125, s11, v25
	v_cvt_pk_fp8_f32 v10, v96, v97
	v_cvt_pk_fp8_f32 v11, v100, v101
	v_cvt_pk_fp8_f32 v12, v104, v105
	v_cvt_pk_fp8_f32 v13, v108, v109
	v_ashrrev_i32_e32 v63, 31, v62
	v_mul_f32_e32 v82, 0x44000000, v82
	v_mul_f32_e32 v83, 0x44000000, v83
	v_mul_f32_e32 v86, 0x44000000, v86
	v_mul_f32_e32 v87, 0x44000000, v87
	v_mul_f32_e32 v90, 0x44000000, v90
	v_mul_f32_e32 v91, 0x44000000, v91
	v_mul_f32_e32 v94, 0x44000000, v94
	v_mul_f32_e32 v95, 0x44000000, v95
	v_med3_f32 v66, v66, s11, v25
	v_med3_f32 v67, v67, s11, v25
	v_med3_f32 v70, v70, s11, v25
	v_med3_f32 v71, v71, s11, v25
	v_med3_f32 v74, v74, s11, v25
	v_med3_f32 v75, v75, s11, v25
	v_med3_f32 v78, v78, s11, v25
	v_med3_f32 v79, v79, s11, v25
	v_cvt_pk_fp8_f32 v14, v112, v113
	v_cvt_pk_fp8_f32 v15, v116, v117
	v_cvt_pk_fp8_f32 v16, v120, v121
	v_cvt_pk_fp8_f32 v17, v124, v125
	v_lshlrev_b64 v[62:63], 12, v[62:63]
	v_mul_f32_e32 v98, 0x44000000, v98
	v_mul_f32_e32 v99, 0x44000000, v99
	v_mul_f32_e32 v102, 0x44000000, v102
	v_mul_f32_e32 v103, 0x44000000, v103
	v_mul_f32_e32 v106, 0x44000000, v106
	v_mul_f32_e32 v107, 0x44000000, v107
	v_mul_f32_e32 v110, 0x44000000, v110
	v_mul_f32_e32 v111, 0x44000000, v111
	v_med3_f32 v82, v82, s11, v25
	v_med3_f32 v83, v83, s11, v25
	v_med3_f32 v86, v86, s11, v25
	v_med3_f32 v87, v87, s11, v25
	v_med3_f32 v90, v90, s11, v25
	v_med3_f32 v91, v91, s11, v25
	v_med3_f32 v94, v94, s11, v25
	v_med3_f32 v95, v95, s11, v25
	v_cvt_pk_fp8_f32 v2, v66, v67 op_sel:[0,0,1]
	v_cvt_pk_fp8_f32 v3, v70, v71 op_sel:[0,0,1]
	v_cvt_pk_fp8_f32 v4, v74, v75 op_sel:[0,0,1]
	v_cvt_pk_fp8_f32 v5, v78, v79 op_sel:[0,0,1]
	s_ashr_i32 s3, s2, 31
	v_lshl_add_u64 v[62:63], s[24:25], 0, v[62:63]
	v_mul_f32_e32 v114, 0x44000000, v114
	v_mul_f32_e32 v115, 0x44000000, v115
	v_mul_f32_e32 v118, 0x44000000, v118
	v_mul_f32_e32 v119, 0x44000000, v119
	v_mul_f32_e32 v122, 0x44000000, v122
	v_mul_f32_e32 v123, 0x44000000, v123
	s_waitcnt lgkmcnt(0)
	v_mul_f32_e32 v126, 0x44000000, v126
	v_mul_f32_e32 v127, 0x44000000, v127
	v_med3_f32 v98, v98, s11, v25
	v_med3_f32 v99, v99, s11, v25
	v_med3_f32 v102, v102, s11, v25
	v_med3_f32 v103, v103, s11, v25
	v_med3_f32 v106, v106, s11, v25
	v_med3_f32 v107, v107, s11, v25
	v_med3_f32 v110, v110, s11, v25
	v_med3_f32 v111, v111, s11, v25
	v_cvt_pk_fp8_f32 v6, v82, v83 op_sel:[0,0,1]
	v_cvt_pk_fp8_f32 v7, v86, v87 op_sel:[0,0,1]
	v_cvt_pk_fp8_f32 v8, v90, v91 op_sel:[0,0,1]
	v_cvt_pk_fp8_f32 v9, v94, v95 op_sel:[0,0,1]
	v_lshl_add_u64 v[62:63], v[62:63], 0, s[2:3]
	v_med3_f32 v114, v114, s11, v25
	v_med3_f32 v115, v115, s11, v25
	v_med3_f32 v118, v118, s11, v25
	v_med3_f32 v119, v119, s11, v25
	v_med3_f32 v122, v122, s11, v25
	v_med3_f32 v123, v123, s11, v25
	v_med3_f32 v126, v126, s11, v25
	v_med3_f32 v127, v127, s11, v25
	v_cvt_pk_fp8_f32 v10, v98, v99 op_sel:[0,0,1]
	v_cvt_pk_fp8_f32 v11, v102, v103 op_sel:[0,0,1]
	v_cvt_pk_fp8_f32 v12, v106, v107 op_sel:[0,0,1]
	v_cvt_pk_fp8_f32 v13, v110, v111 op_sel:[0,0,1]
	v_lshl_add_u64 v[62:63], v[62:63], 0, v[18:19]
	v_cvt_pk_fp8_f32 v14, v114, v115 op_sel:[0,0,1]
	v_cvt_pk_fp8_f32 v15, v118, v119 op_sel:[0,0,1]
	v_cvt_pk_fp8_f32 v16, v122, v123 op_sel:[0,0,1]
	v_cvt_pk_fp8_f32 v17, v126, v127 op_sel:[0,0,1]
	global_store_dwordx4 v[62:63], v[2:5], off
	global_store_dwordx4 v[62:63], v[6:9], off offset:32
	global_store_dwordx4 v[62:63], v[10:13], off offset:64
	global_store_dwordx4 v[62:63], v[14:17], off offset:96
	s_waitcnt lgkmcnt(0)
	s_add_i32 s1, s1, s8
	s_add_i32 s9, s9, s0
	s_cmp_lt_i32 s1, s99
	s_cbranch_scc1 .LBB0_550
.LBB0_551:
	s_cmp_lg_u32 s101, 0
	s_cbranch_scc1 .Lq_done
	s_mov_b32 s101, 1
	s_cmpk_lt_i32 s100, 0x600
	s_cbranch_scc1 .Lq_done
	s_add_i32 s1, s100, 0x1d00
	s_movk_i32 s8, 0x100
	s_movk_i32 s0, 0x2000
	s_lshl_b32 s9, s1, 5
	s_movk_i32 s99, 0x2b00
	s_branch .LBB0_550

; __global__ void __launch_bounds__(NWAVES * 64, 2) mk_fwd(Args args) {
	.amdhsa_kernel _Z6mk_fwd4Args
		.amdhsa_group_segment_fixed_size 0
		.amdhsa_private_segment_fixed_size 0
		.amdhsa_kernarg_size 472
		.amdhsa_user_sgpr_count 2
		.amdhsa_user_sgpr_dispatch_ptr 0
		.amdhsa_user_sgpr_queue_ptr 0
		.amdhsa_user_sgpr_kernarg_segment_ptr 1
		.amdhsa_user_sgpr_dispatch_id 0
		.amdhsa_user_sgpr_kernarg_preload_length 0
		.amdhsa_user_sgpr_kernarg_preload_offset 0
		.amdhsa_user_sgpr_private_segment_size 0
		.amdhsa_uses_dynamic_stack 0
		.amdhsa_enable_private_segment 0
		.amdhsa_system_sgpr_workgroup_id_x 1
		.amdhsa_system_sgpr_workgroup_id_y 0
		.amdhsa_system_sgpr_workgroup_id_z 0
		.amdhsa_system_sgpr_workgroup_info 0
		.amdhsa_system_vgpr_workitem_id 0
		.amdhsa_next_free_vgpr 253
		.amdhsa_next_free_sgpr 102
		.amdhsa_accum_offset 256
		.amdhsa_reserve_vcc 1
		.amdhsa_float_round_mode_32 0
		.amdhsa_float_round_mode_16_64 0
		.amdhsa_float_denorm_mode_32 3
		.amdhsa_float_denorm_mode_16_64 3
		.amdhsa_dx10_clamp 1
		.amdhsa_ieee_mode 1
		.amdhsa_fp16_overflow 0
		.amdhsa_tg_split 0
		.amdhsa_exception_fp_ieee_invalid_op 0
		.amdhsa_exception_fp_denorm_src 0
		.amdhsa_exception_fp_ieee_div_zero 0
		.amdhsa_exception_fp_ieee_overflow 0
		.amdhsa_exception_fp_ieee_underflow 0
		.amdhsa_exception_fp_ieee_inexact 0
		.amdhsa_exception_int_div_zero 0
	.end_amdhsa_kernel

; __global__ void __launch_bounds__(NWAVES * 64, 2) mk_fwd(Args args) {
.Lfunc_end0:
	.size	_Z6mk_fwd4Args, .Lfunc_end0-_Z6mk_fwd4Args
	.set _Z6mk_fwd4Args.num_vgpr, 253
	.set _Z6mk_fwd4Args.num_agpr, 0
	.set _Z6mk_fwd4Args.numbered_sgpr, 102
	.set _Z6mk_fwd4Args.num_named_barrier, 0
	.set _Z6mk_fwd4Args.private_seg_size, 0
	.set _Z6mk_fwd4Args.uses_vcc, 1
	.set _Z6mk_fwd4Args.uses_flat_scratch, 0
	.set _Z6mk_fwd4Args.has_dyn_sized_stack, 0
	.set _Z6mk_fwd4Args.has_recursion, 0
	.set _Z6mk_fwd4Args.has_indirect_call, 0

; __global__ void __launch_bounds__(NWAVES * 64, 2) mk_fwd(Args args) {
amdhsa.kernels:
  - .agpr_count:     0
    .args:
      - .offset:         0
        .size:           216
        .value_kind:     by_value
      - .offset:         216
        .size:           4
        .value_kind:     hidden_block_count_x
      - .offset:         220
        .size:           4
        .value_kind:     hidden_block_count_y
      - .offset:         224
        .size:           4
        .value_kind:     hidden_block_count_z
      - .offset:         228
        .size:           2
        .value_kind:     hidden_group_size_x
      - .offset:         230
        .size:           2
        .value_kind:     hidden_group_size_y
      - .offset:         232
        .size:           2
        .value_kind:     hidden_group_size_z
      - .offset:         234
        .size:           2
        .value_kind:     hidden_remainder_x
      - .offset:         236
        .size:           2
        .value_kind:     hidden_remainder_y
      - .offset:         238
        .size:           2
        .value_kind:     hidden_remainder_z
      - .offset:         256
        .size:           8
        .value_kind:     hidden_global_offset_x
      - .offset:         264
        .size:           8
        .value_kind:     hidden_global_offset_y
      - .offset:         272
        .size:           8
        .value_kind:     hidden_global_offset_z
      - .offset:         280
        .size:           2
        .value_kind:     hidden_grid_dims
      - .offset:         336
        .size:           4
        .value_kind:     hidden_dynamic_lds_size
    .group_segment_fixed_size: 0
    .kernarg_segment_align: 8
    .kernarg_segment_size: 472
    .language:       OpenCL C
    .language_version:
      - 2
      - 0
    .max_flat_workgroup_size: 512
    .name:           _Z6mk_fwd4Args
    .private_segment_fixed_size: 0
    .sgpr_count:     108
    .sgpr_spill_count: 47
    .symbol:         _Z6mk_fwd4Args.kd
    .uniform_work_group_size: 1
    .uses_dynamic_stack: false
    .vgpr_count:     253
    .vgpr_spill_count: 0
    .wavefront_size: 64
